# init phase x->bf16 copy loop hand-unrolled 6x (6 loads in flight per wave instead of 1), saddr addressing
# speedup vs baseline: 1.0093x; 1.0038x over previous
; #define TIDX opaque_tid()
; #define BIDX opaque_bid()
; DEVI void tconv_seg(const float* src, int ld, int krows, int c0, int ncols, int ndst, bf16_t* dst, int dld,
;                     char* smem) {
;   float* tile = (float*)smem;
;   const int tid = TIDX;
;   const int nkt = krows >> 6, nnt = (ndst + 63) >> 6;
;   const int lr = tid >> 4, lc = (tid & 15) * 4;
;   const int kp = tid & 31, wn = tid >> 5;
;   for (int t = BIDX; t < nkt * nnt; t += gridDim.x) {
;     const int kt = t % nkt, nt = t / nkt;
;     const int k0 = kt * 64, n0 = nt * 64;
; DEVI void init_phase(const Params& p) {
;   const int gt = BIDX * 256 + TIDX, nth = gridDim.x * 256;
;   if (gt < 64) ((int*)(p.ws + OFF_MISC))[gt] = 0;
;   bf16_t* hb = (bf16_t*)(p.ws + OFF_HB);
;   for (int idx = gt; idx < L * 256; idx += nth) {
;     const int t = idx >> 8, c = (idx & 255) * 4;
;     f32x4 v = (t < 16) ? *(const f32x4*)(p.in[1] + t * 1024 + c) : *(const f32x4*)(p.in[0] + (size_t)(t - 16) * 1024 + c);
;     if (t < 16) *(f32x4*)(hfrow(p, t) + c) = v;
;     *(u32x2*)(hb + (size_t)t * 1024 + c) = u32x2{pack2(v[0], v[1]), pack2(v[2], v[3])};
;   }
; }
.LBB0_1919:
	s_or_b64 exec, exec, s[0:1]
	s_mov_b64 s[6:7], exec
	v_readlane_b32 s68, v248, 63
	v_readlane_b32 s69, v247, 0
	v_readlane_b32 s70, v247, 1
	v_readlane_b32 s71, v247, 2
	s_add_u32 s10, s14, 0x3a80000
	s_addc_u32 s11, s15, 0
	s_movk_i32 s0, 0x1000
	v_cmp_gt_u32_e32 vcc, s0, v6
	s_and_saveexec_b64 s[0:1], vcc
	s_cbranch_execz .Lmy_init_main
	v_lshlrev_b32_e32 v0, 4, v6
	v_lshlrev_b32_e32 v7, 3, v6
	global_load_dwordx4 v[8:11], v0, s[70:71]
	s_waitcnt vmcnt(0)
	global_store_dwordx4 v0, v[8:11], s[10:11]
	v_cvt_pk_bf16_f32 v2, v8, v9
	v_cvt_pk_bf16_f32 v3, v10, v11
	global_store_dwordx2 v7, v[2:3], s[14:15]
.Lmy_init_main:
	s_or_b64 exec, exec, s[0:1]
	s_add_u32 s24, s14, 0x8000
	s_addc_u32 s25, s15, 0
	v_readfirstlane_b32 s0, v6
	s_lshl_b32 s1, s48, 8
	s_lshl_b32 s16, s48, 12
	s_lshl_b32 s17, s48, 11
	s_mul_i32 s5, s1, 5
	v_lshlrev_b32_e32 v12, 4, v6
	v_lshlrev_b32_e32 v13, 3, v6
.Lmy_init_loop:
	s_add_u32 s0, s0, s5
	s_cmp_lt_u32 s0, 0x400000
	s_cbranch_scc0 .Lmy_init_tailpre
	global_load_dwordx4 v[14:17], v12, s[68:69]
	v_add_u32_e32 v8, s16, v12
	global_load_dwordx4 v[18:21], v8, s[68:69]
	v_add_u32_e32 v8, s16, v8
	global_load_dwordx4 v[22:25], v8, s[68:69]
	v_add_u32_e32 v8, s16, v8
	global_load_dwordx4 v[26:29], v8, s[68:69]
	v_add_u32_e32 v8, s16, v8
	global_load_dwordx4 v[30:33], v8, s[68:69]
	v_add_u32_e32 v8, s16, v8
	global_load_dwordx4 v[34:37], v8, s[68:69]
	v_add_u32_e32 v12, s16, v8
	s_waitcnt vmcnt(5)
	v_cvt_pk_bf16_f32 v14, v14, v15
	v_cvt_pk_bf16_f32 v15, v16, v17
	s_waitcnt vmcnt(4)
	v_cvt_pk_bf16_f32 v18, v18, v19
	v_cvt_pk_bf16_f32 v19, v20, v21
	s_waitcnt vmcnt(3)
	v_cvt_pk_bf16_f32 v22, v22, v23
	v_cvt_pk_bf16_f32 v23, v24, v25
	s_waitcnt vmcnt(2)
	v_cvt_pk_bf16_f32 v26, v26, v27
	v_cvt_pk_bf16_f32 v27, v28, v29
	s_waitcnt vmcnt(1)
	v_cvt_pk_bf16_f32 v30, v30, v31
	v_cvt_pk_bf16_f32 v31, v32, v33
	s_waitcnt vmcnt(0)
	v_cvt_pk_bf16_f32 v34, v34, v35
	v_cvt_pk_bf16_f32 v35, v36, v37
	global_store_dwordx2 v13, v[14:15], s[24:25]
	v_add_u32_e32 v13, s17, v13
	global_store_dwordx2 v13, v[18:19], s[24:25]
	v_add_u32_e32 v13, s17, v13
	global_store_dwordx2 v13, v[22:23], s[24:25]
	v_add_u32_e32 v13, s17, v13
	global_store_dwordx2 v13, v[26:27], s[24:25]
	v_add_u32_e32 v13, s17, v13
	global_store_dwordx2 v13, v[30:31], s[24:25]
	v_add_u32_e32 v13, s17, v13
	global_store_dwordx2 v13, v[34:35], s[24:25]
	v_add_u32_e32 v13, s17, v13
	s_add_u32 s0, s0, s1
	s_branch .Lmy_init_loop
.Lmy_init_tailpre:
	s_sub_u32 s0, s0, s5
.Lmy_init_tail:
	s_cmp_lt_u32 s0, 0x400000
	s_cbranch_scc0 .Lmy_init_done
	global_load_dwordx4 v[14:17], v12, s[68:69]
	v_add_u32_e32 v12, s16, v12
	s_waitcnt vmcnt(0)
	v_cvt_pk_bf16_f32 v14, v14, v15
	v_cvt_pk_bf16_f32 v15, v16, v17
	global_store_dwordx2 v13, v[14:15], s[24:25]
	v_add_u32_e32 v13, s17, v13
	s_add_u32 s0, s0, s1
	s_branch .Lmy_init_tail
.Lmy_init_done:
.LBB0_1928:
	s_or_b64 exec, exec, s[6:7]
	v_mov_b32_e32 v2, v206
	s_mov_b32 s5, s88
	s_cmpk_gt_i32 s5, 0x1ff
	s_cbranch_scc1 .LBB0_1951
	v_ashrrev_i32_e32 v0, 4, v2
	v_lshlrev_b32_e32 v6, 2, v2
	v_ashrrev_i32_e32 v17, 5, v2
	v_lshlrev_b32_e32 v2, 1, v2
	v_and_b32_e32 v18, 62, v2
	v_mul_u32_u24_e32 v2, 0x104, v18
	v_and_b32_e32 v8, 48, v6
	s_movk_i32 s0, 0x104
	v_lshlrev_b32_e32 v3, 2, v17
	v_and_b32_e32 v16, 60, v6
	v_readlane_b32 s68, v248, 63
	v_mul_lo_u32 v9, v0, s0
	v_add3_u32 v19, 32, v2, v3
	v_and_or_b32 v2, v17, 15, v8
	v_readlane_b32 s0, v247, 19
	v_lshlrev_b32_e32 v4, 2, v16
	v_mov_b32_e32 v5, v1
	v_readlane_b32 s74, v247, 5
	v_readlane_b32 s75, v247, 6
	v_lshlrev_b32_e32 v2, 4, v2
	v_mov_b32_e32 v3, v1
	v_readlane_b32 s1, v247, 20
	v_add_u32_e32 v7, 32, v4
	v_lshl_add_u64 v[10:11], s[74:75], 0, v[4:5]
	v_lshl_add_u64 v[2:3], s[0:1], 0, v[2:3]
	v_and_b32_e32 v4, 12, v6
	v_add_u32_e32 v20, 8, v17
	v_lshl_add_u64 v[12:13], v[2:3], 0, v[4:5]
	v_and_or_b32 v2, v20, 15, v8
	v_lshlrev_b32_e32 v2, 4, v2
	v_mov_b32_e32 v3, v1
	v_lshl_add_u64 v[2:3], s[0:1], 0, v[2:3]
	v_lshl_add_u64 v[14:15], v[2:3], 0, v[4:5]
	s_lshl_b32 s9, s5, 6
	s_lshl_b32 s10, s48, 6
	v_add_u32_e32 v21, v7, v9
	v_readlane_b32 s69, v247, 0
	v_readlane_b32 s70, v247, 1
	v_readlane_b32 s71, v247, 2
	v_readlane_b32 s72, v247, 3
	v_readlane_b32 s73, v247, 4
	v_readlane_b32 s76, v247, 7
	v_readlane_b32 s77, v247, 8
	v_readlane_b32 s78, v247, 9
	v_readlane_b32 s79, v247, 10
	v_readlane_b32 s80, v247, 11
	v_readlane_b32 s81, v247, 12
	v_readlane_b32 s82, v247, 13
	v_readlane_b32 s83, v247, 14
	s_branch .LBB0_1931
